# prologue: gain-folded weight transposes (in-proj, up-proj) issue their 32 weight + 32 gain loads together with counted waits instead of one load per vmcnt(0)
# speedup vs baseline: 1.0263x; 1.0053x over previous
.LBB0_36:
	v_lshl_add_u64 v[40:41], v[38:39], 0, s[28:29]
	global_load_dword v84, v[40:41], off
	v_lshl_add_u64 v[40:41], v[34:35], 0, s[28:29]
	global_load_dword v85, v[40:41], off
	v_lshl_add_u64 v[40:41], v[32:33], 0, s[28:29]
	global_load_dword v86, v[40:41], off
	v_lshl_add_u64 v[40:41], v[30:31], 0, s[28:29]
	global_load_dword v87, v[40:41], off
	v_lshl_add_u64 v[40:41], v[28:29], 0, s[28:29]
	global_load_dword v88, v[40:41], off
	v_lshl_add_u64 v[40:41], v[26:27], 0, s[28:29]
	global_load_dword v89, v[40:41], off
	v_lshl_add_u64 v[40:41], v[24:25], 0, s[28:29]
	global_load_dword v90, v[40:41], off
	v_lshl_add_u64 v[40:41], v[16:17], 0, s[28:29]
	global_load_dword v91, v[40:41], off
	s_add_u32 s28, s28, 0x40000
	s_addc_u32 s29, s29, 0
	v_lshl_add_u64 v[40:41], v[38:39], 0, s[28:29]
	global_load_dword v92, v[40:41], off
	v_lshl_add_u64 v[40:41], v[34:35], 0, s[28:29]
	global_load_dword v93, v[40:41], off
	v_lshl_add_u64 v[40:41], v[32:33], 0, s[28:29]
	global_load_dword v94, v[40:41], off
	v_lshl_add_u64 v[40:41], v[30:31], 0, s[28:29]
	global_load_dword v95, v[40:41], off
	v_lshl_add_u64 v[40:41], v[28:29], 0, s[28:29]
	global_load_dword v96, v[40:41], off
	v_lshl_add_u64 v[40:41], v[26:27], 0, s[28:29]
	global_load_dword v97, v[40:41], off
	v_lshl_add_u64 v[40:41], v[24:25], 0, s[28:29]
	global_load_dword v98, v[40:41], off
	v_lshl_add_u64 v[40:41], v[16:17], 0, s[28:29]
	global_load_dword v99, v[40:41], off
	s_add_u32 s28, s28, 0x40000
	s_addc_u32 s29, s29, 0
	v_lshl_add_u64 v[40:41], v[38:39], 0, s[28:29]
	global_load_dword v100, v[40:41], off
	v_lshl_add_u64 v[40:41], v[34:35], 0, s[28:29]
	global_load_dword v101, v[40:41], off
	v_lshl_add_u64 v[40:41], v[32:33], 0, s[28:29]
	global_load_dword v102, v[40:41], off
	v_lshl_add_u64 v[40:41], v[30:31], 0, s[28:29]
	global_load_dword v103, v[40:41], off
	v_lshl_add_u64 v[40:41], v[28:29], 0, s[28:29]
	global_load_dword v104, v[40:41], off
	v_lshl_add_u64 v[40:41], v[26:27], 0, s[28:29]
	global_load_dword v105, v[40:41], off
	v_lshl_add_u64 v[40:41], v[24:25], 0, s[28:29]
	global_load_dword v106, v[40:41], off
	v_lshl_add_u64 v[40:41], v[16:17], 0, s[28:29]
	global_load_dword v107, v[40:41], off
	s_add_u32 s28, s28, 0x40000
	s_addc_u32 s29, s29, 0
	v_lshl_add_u64 v[40:41], v[38:39], 0, s[28:29]
	global_load_dword v108, v[40:41], off
	v_lshl_add_u64 v[40:41], v[34:35], 0, s[28:29]
	global_load_dword v109, v[40:41], off
	v_lshl_add_u64 v[40:41], v[32:33], 0, s[28:29]
	global_load_dword v110, v[40:41], off
	v_lshl_add_u64 v[40:41], v[30:31], 0, s[28:29]
	global_load_dword v111, v[40:41], off
	v_lshl_add_u64 v[40:41], v[28:29], 0, s[28:29]
	global_load_dword v112, v[40:41], off
	v_lshl_add_u64 v[40:41], v[26:27], 0, s[28:29]
	global_load_dword v113, v[40:41], off
	v_lshl_add_u64 v[40:41], v[24:25], 0, s[28:29]
	global_load_dword v114, v[40:41], off
	v_lshl_add_u64 v[40:41], v[16:17], 0, s[28:29]
	global_load_dword v115, v[40:41], off
	s_add_u32 s28, s28, 0x40000
	s_addc_u32 s29, s29, 0
	s_andn2_b64 vcc, exec, s[30:31]
	s_cbranch_vccnz .Lwp_up_ng
	v_lshl_add_u64 v[40:41], v[22:23], 0, s[6:7]
	global_load_dword v116, v[40:41], off
	global_load_dword v117, v[40:41], off offset:8
	global_load_dword v118, v[40:41], off offset:16
	global_load_dword v119, v[40:41], off offset:24
	global_load_dword v120, v[40:41], off offset:32
	global_load_dword v121, v[40:41], off offset:40
	global_load_dword v122, v[40:41], off offset:48
	global_load_dword v123, v[40:41], off offset:56
	global_load_dword v124, v[40:41], off offset:64
	global_load_dword v125, v[40:41], off offset:72
	global_load_dword v126, v[40:41], off offset:80
	global_load_dword v127, v[40:41], off offset:88
	global_load_dword v128, v[40:41], off offset:96
	global_load_dword v129, v[40:41], off offset:104
	global_load_dword v130, v[40:41], off offset:112
	global_load_dword v131, v[40:41], off offset:120
	global_load_dword v132, v[40:41], off offset:128
	global_load_dword v133, v[40:41], off offset:136
	global_load_dword v134, v[40:41], off offset:144
	global_load_dword v135, v[40:41], off offset:152
	global_load_dword v136, v[40:41], off offset:160
	global_load_dword v137, v[40:41], off offset:168
	global_load_dword v138, v[40:41], off offset:176
	global_load_dword v139, v[40:41], off offset:184
	global_load_dword v140, v[40:41], off offset:192
	global_load_dword v141, v[40:41], off offset:200
	global_load_dword v142, v[40:41], off offset:208
	global_load_dword v143, v[40:41], off offset:216
	global_load_dword v144, v[40:41], off offset:224
	global_load_dword v145, v[40:41], off offset:232
	global_load_dword v146, v[40:41], off offset:240
	global_load_dword v147, v[40:41], off offset:248
	s_waitcnt vmcnt(31)
	v_mul_f32_e32 v13, v116, v84
	ds_write_b32 v4, v13
	s_waitcnt vmcnt(30)
	v_mul_f32_e32 v13, v117, v85
	ds_write_b32 v4, v13 offset:264
	s_waitcnt vmcnt(29)
	v_mul_f32_e32 v13, v118, v86
	ds_write_b32 v4, v13 offset:528
	s_waitcnt vmcnt(28)
	v_mul_f32_e32 v13, v119, v87
	ds_write_b32 v4, v13 offset:792
	s_waitcnt vmcnt(27)
	v_mul_f32_e32 v13, v120, v88
	ds_write_b32 v4, v13 offset:1056
	s_waitcnt vmcnt(26)
	v_mul_f32_e32 v13, v121, v89
	ds_write_b32 v4, v13 offset:1320
	s_waitcnt vmcnt(25)
	v_mul_f32_e32 v13, v122, v90
	ds_write_b32 v4, v13 offset:1584
	s_waitcnt vmcnt(24)
	v_mul_f32_e32 v13, v123, v91
	ds_write_b32 v4, v13 offset:1848
	s_waitcnt vmcnt(23)
	v_mul_f32_e32 v13, v124, v92
	ds_write_b32 v4, v13 offset:2112
	s_waitcnt vmcnt(22)
	v_mul_f32_e32 v13, v125, v93
	ds_write_b32 v4, v13 offset:2376
	s_waitcnt vmcnt(21)
	v_mul_f32_e32 v13, v126, v94
	ds_write_b32 v4, v13 offset:2640
	s_waitcnt vmcnt(20)
	v_mul_f32_e32 v13, v127, v95
	ds_write_b32 v4, v13 offset:2904
	s_waitcnt vmcnt(19)
	v_mul_f32_e32 v13, v128, v96
	ds_write_b32 v4, v13 offset:3168
	s_waitcnt vmcnt(18)
	v_mul_f32_e32 v13, v129, v97
	ds_write_b32 v4, v13 offset:3432
	s_waitcnt vmcnt(17)
	v_mul_f32_e32 v13, v130, v98
	ds_write_b32 v4, v13 offset:3696
	s_waitcnt vmcnt(16)
	v_mul_f32_e32 v13, v131, v99
	ds_write_b32 v4, v13 offset:3960
	s_waitcnt vmcnt(15)
	v_mul_f32_e32 v13, v132, v100
	ds_write_b32 v4, v13 offset:4224
	s_waitcnt vmcnt(14)
	v_mul_f32_e32 v13, v133, v101
	ds_write_b32 v4, v13 offset:4488
	s_waitcnt vmcnt(13)
	v_mul_f32_e32 v13, v134, v102
	ds_write_b32 v4, v13 offset:4752
	s_waitcnt vmcnt(12)
	v_mul_f32_e32 v13, v135, v103
	ds_write_b32 v4, v13 offset:5016
	s_waitcnt vmcnt(11)
	v_mul_f32_e32 v13, v136, v104
	ds_write_b32 v4, v13 offset:5280
	s_waitcnt vmcnt(10)
	v_mul_f32_e32 v13, v137, v105
	ds_write_b32 v4, v13 offset:5544
	s_waitcnt vmcnt(9)
	v_mul_f32_e32 v13, v138, v106
	ds_write_b32 v4, v13 offset:5808
	s_waitcnt vmcnt(8)
	v_mul_f32_e32 v13, v139, v107
	ds_write_b32 v4, v13 offset:6072
	s_waitcnt vmcnt(7)
	v_mul_f32_e32 v13, v140, v108
	ds_write_b32 v4, v13 offset:6336
	s_waitcnt vmcnt(6)
	v_mul_f32_e32 v13, v141, v109
	ds_write_b32 v4, v13 offset:6600
	s_waitcnt vmcnt(5)
	v_mul_f32_e32 v13, v142, v110
	ds_write_b32 v4, v13 offset:6864
	s_waitcnt vmcnt(4)
	v_mul_f32_e32 v13, v143, v111
	ds_write_b32 v4, v13 offset:7128
	s_waitcnt vmcnt(3)
	v_mul_f32_e32 v13, v144, v112
	ds_write_b32 v4, v13 offset:7392
	s_waitcnt vmcnt(2)
	v_mul_f32_e32 v13, v145, v113
	ds_write_b32 v4, v13 offset:7656
	s_waitcnt vmcnt(1)
	v_mul_f32_e32 v13, v146, v114
	ds_write_b32 v4, v13 offset:7920
	s_waitcnt vmcnt(0)
	v_mul_f32_e32 v13, v147, v115
	ds_write_b32 v4, v13 offset:8184
	s_branch .LBB0_52
.Lwp_up_ng:
	s_waitcnt vmcnt(31)
	v_mul_f32_e32 v13, 1.0, v84
	ds_write_b32 v4, v13
	s_waitcnt vmcnt(30)
	v_mul_f32_e32 v13, 1.0, v85
	ds_write_b32 v4, v13 offset:264
	s_waitcnt vmcnt(29)
	v_mul_f32_e32 v13, 1.0, v86
	ds_write_b32 v4, v13 offset:528
	s_waitcnt vmcnt(28)
	v_mul_f32_e32 v13, 1.0, v87
	ds_write_b32 v4, v13 offset:792
	s_waitcnt vmcnt(27)
	v_mul_f32_e32 v13, 1.0, v88
	ds_write_b32 v4, v13 offset:1056
	s_waitcnt vmcnt(26)
	v_mul_f32_e32 v13, 1.0, v89
	ds_write_b32 v4, v13 offset:1320
	s_waitcnt vmcnt(25)
	v_mul_f32_e32 v13, 1.0, v90
	ds_write_b32 v4, v13 offset:1584
	s_waitcnt vmcnt(24)
	v_mul_f32_e32 v13, 1.0, v91
	ds_write_b32 v4, v13 offset:1848
	s_waitcnt vmcnt(23)
	v_mul_f32_e32 v13, 1.0, v92
	ds_write_b32 v4, v13 offset:2112
	s_waitcnt vmcnt(22)
	v_mul_f32_e32 v13, 1.0, v93
	ds_write_b32 v4, v13 offset:2376
	s_waitcnt vmcnt(21)
	v_mul_f32_e32 v13, 1.0, v94
	ds_write_b32 v4, v13 offset:2640
	s_waitcnt vmcnt(20)
	v_mul_f32_e32 v13, 1.0, v95
	ds_write_b32 v4, v13 offset:2904
	s_waitcnt vmcnt(19)
	v_mul_f32_e32 v13, 1.0, v96
	ds_write_b32 v4, v13 offset:3168
	s_waitcnt vmcnt(18)
	v_mul_f32_e32 v13, 1.0, v97
	ds_write_b32 v4, v13 offset:3432
	s_waitcnt vmcnt(17)
	v_mul_f32_e32 v13, 1.0, v98
	ds_write_b32 v4, v13 offset:3696
	s_waitcnt vmcnt(16)
	v_mul_f32_e32 v13, 1.0, v99
	ds_write_b32 v4, v13 offset:3960
	s_waitcnt vmcnt(15)
	v_mul_f32_e32 v13, 1.0, v100
	ds_write_b32 v4, v13 offset:4224
	s_waitcnt vmcnt(14)
	v_mul_f32_e32 v13, 1.0, v101
	ds_write_b32 v4, v13 offset:4488
	s_waitcnt vmcnt(13)
	v_mul_f32_e32 v13, 1.0, v102
	ds_write_b32 v4, v13 offset:4752
	s_waitcnt vmcnt(12)
	v_mul_f32_e32 v13, 1.0, v103
	ds_write_b32 v4, v13 offset:5016
	s_waitcnt vmcnt(11)
	v_mul_f32_e32 v13, 1.0, v104
	ds_write_b32 v4, v13 offset:5280
	s_waitcnt vmcnt(10)
	v_mul_f32_e32 v13, 1.0, v105
	ds_write_b32 v4, v13 offset:5544
	s_waitcnt vmcnt(9)
	v_mul_f32_e32 v13, 1.0, v106
	ds_write_b32 v4, v13 offset:5808
	s_waitcnt vmcnt(8)
	v_mul_f32_e32 v13, 1.0, v107
	ds_write_b32 v4, v13 offset:6072
	s_waitcnt vmcnt(7)
	v_mul_f32_e32 v13, 1.0, v108
	ds_write_b32 v4, v13 offset:6336
	s_waitcnt vmcnt(6)
	v_mul_f32_e32 v13, 1.0, v109
	ds_write_b32 v4, v13 offset:6600
	s_waitcnt vmcnt(5)
	v_mul_f32_e32 v13, 1.0, v110
	ds_write_b32 v4, v13 offset:6864
	s_waitcnt vmcnt(4)
	v_mul_f32_e32 v13, 1.0, v111
	ds_write_b32 v4, v13 offset:7128
	s_waitcnt vmcnt(3)
	v_mul_f32_e32 v13, 1.0, v112
	ds_write_b32 v4, v13 offset:7392
	s_waitcnt vmcnt(2)
	v_mul_f32_e32 v13, 1.0, v113
	ds_write_b32 v4, v13 offset:7656
	s_waitcnt vmcnt(1)
	v_mul_f32_e32 v13, 1.0, v114
	ds_write_b32 v4, v13 offset:7920
	s_waitcnt vmcnt(0)
	v_mul_f32_e32 v13, 1.0, v115
	ds_write_b32 v4, v13 offset:8184
	s_branch .LBB0_52

.LBB0_61:
	v_lshl_add_u64 v[40:41], v[36:37], 0, s[30:31]
	global_load_dword v84, v[40:41], off
	v_lshl_add_u64 v[40:41], v[34:35], 0, s[30:31]
	global_load_dword v85, v[40:41], off
	v_lshl_add_u64 v[40:41], v[32:33], 0, s[30:31]
	global_load_dword v86, v[40:41], off
	v_lshl_add_u64 v[40:41], v[30:31], 0, s[30:31]
	global_load_dword v87, v[40:41], off
	v_lshl_add_u64 v[40:41], v[28:29], 0, s[30:31]
	global_load_dword v88, v[40:41], off
	v_lshl_add_u64 v[40:41], v[26:27], 0, s[30:31]
	global_load_dword v89, v[40:41], off
	v_lshl_add_u64 v[40:41], v[24:25], 0, s[30:31]
	global_load_dword v90, v[40:41], off
	v_lshl_add_u64 v[40:41], v[16:17], 0, s[30:31]
	global_load_dword v91, v[40:41], off
	s_add_u32 s30, s30, 0x2c000
	s_addc_u32 s31, s31, 0
	v_lshl_add_u64 v[40:41], v[36:37], 0, s[30:31]
	global_load_dword v92, v[40:41], off
	v_lshl_add_u64 v[40:41], v[34:35], 0, s[30:31]
	global_load_dword v93, v[40:41], off
	v_lshl_add_u64 v[40:41], v[32:33], 0, s[30:31]
	global_load_dword v94, v[40:41], off
	v_lshl_add_u64 v[40:41], v[30:31], 0, s[30:31]
	global_load_dword v95, v[40:41], off
	v_lshl_add_u64 v[40:41], v[28:29], 0, s[30:31]
	global_load_dword v96, v[40:41], off
	v_lshl_add_u64 v[40:41], v[26:27], 0, s[30:31]
	global_load_dword v97, v[40:41], off
	v_lshl_add_u64 v[40:41], v[24:25], 0, s[30:31]
	global_load_dword v98, v[40:41], off
	v_lshl_add_u64 v[40:41], v[16:17], 0, s[30:31]
	global_load_dword v99, v[40:41], off
	s_add_u32 s30, s30, 0x2c000
	s_addc_u32 s31, s31, 0
	v_lshl_add_u64 v[40:41], v[36:37], 0, s[30:31]
	global_load_dword v100, v[40:41], off
	v_lshl_add_u64 v[40:41], v[34:35], 0, s[30:31]
	global_load_dword v101, v[40:41], off
	v_lshl_add_u64 v[40:41], v[32:33], 0, s[30:31]
	global_load_dword v102, v[40:41], off
	v_lshl_add_u64 v[40:41], v[30:31], 0, s[30:31]
	global_load_dword v103, v[40:41], off
	v_lshl_add_u64 v[40:41], v[28:29], 0, s[30:31]
	global_load_dword v104, v[40:41], off
	v_lshl_add_u64 v[40:41], v[26:27], 0, s[30:31]
	global_load_dword v105, v[40:41], off
	v_lshl_add_u64 v[40:41], v[24:25], 0, s[30:31]
	global_load_dword v106, v[40:41], off
	v_lshl_add_u64 v[40:41], v[16:17], 0, s[30:31]
	global_load_dword v107, v[40:41], off
	s_add_u32 s30, s30, 0x2c000
	s_addc_u32 s31, s31, 0
	v_lshl_add_u64 v[40:41], v[36:37], 0, s[30:31]
	global_load_dword v108, v[40:41], off
	v_lshl_add_u64 v[40:41], v[34:35], 0, s[30:31]
	global_load_dword v109, v[40:41], off
	v_lshl_add_u64 v[40:41], v[32:33], 0, s[30:31]
	global_load_dword v110, v[40:41], off
	v_lshl_add_u64 v[40:41], v[30:31], 0, s[30:31]
	global_load_dword v111, v[40:41], off
	v_lshl_add_u64 v[40:41], v[28:29], 0, s[30:31]
	global_load_dword v112, v[40:41], off
	v_lshl_add_u64 v[40:41], v[26:27], 0, s[30:31]
	global_load_dword v113, v[40:41], off
	v_lshl_add_u64 v[40:41], v[24:25], 0, s[30:31]
	global_load_dword v114, v[40:41], off
	v_lshl_add_u64 v[40:41], v[16:17], 0, s[30:31]
	global_load_dword v115, v[40:41], off
	s_add_u32 s30, s30, 0x2c000
	s_addc_u32 s31, s31, 0
	s_andn2_b64 vcc, exec, s[36:37]
	s_cbranch_vccnz .Lwp_in_ng
	v_lshl_add_u64 v[40:41], v[22:23], 0, s[6:7]
	global_load_dword v116, v[40:41], off
	global_load_dword v117, v[40:41], off offset:8
	global_load_dword v118, v[40:41], off offset:16
	global_load_dword v119, v[40:41], off offset:24
	global_load_dword v120, v[40:41], off offset:32
	global_load_dword v121, v[40:41], off offset:40
	global_load_dword v122, v[40:41], off offset:48
	global_load_dword v123, v[40:41], off offset:56
	global_load_dword v124, v[40:41], off offset:64
	global_load_dword v125, v[40:41], off offset:72
	global_load_dword v126, v[40:41], off offset:80
	global_load_dword v127, v[40:41], off offset:88
	global_load_dword v128, v[40:41], off offset:96
	global_load_dword v129, v[40:41], off offset:104
	global_load_dword v130, v[40:41], off offset:112
	global_load_dword v131, v[40:41], off offset:120
	global_load_dword v132, v[40:41], off offset:128
	global_load_dword v133, v[40:41], off offset:136
	global_load_dword v134, v[40:41], off offset:144
	global_load_dword v135, v[40:41], off offset:152
	global_load_dword v136, v[40:41], off offset:160
	global_load_dword v137, v[40:41], off offset:168
	global_load_dword v138, v[40:41], off offset:176
	global_load_dword v139, v[40:41], off offset:184
	global_load_dword v140, v[40:41], off offset:192
	global_load_dword v141, v[40:41], off offset:200
	global_load_dword v142, v[40:41], off offset:208
	global_load_dword v143, v[40:41], off offset:216
	global_load_dword v144, v[40:41], off offset:224
	global_load_dword v145, v[40:41], off offset:232
	global_load_dword v146, v[40:41], off offset:240
	global_load_dword v147, v[40:41], off offset:248
	s_waitcnt vmcnt(31)
	v_mul_f32_e32 v13, v116, v84
	ds_write_b32 v4, v13
	s_waitcnt vmcnt(30)
	v_mul_f32_e32 v13, v117, v85
	ds_write_b32 v4, v13 offset:264
	s_waitcnt vmcnt(29)
	v_mul_f32_e32 v13, v118, v86
	ds_write_b32 v4, v13 offset:528
	s_waitcnt vmcnt(28)
	v_mul_f32_e32 v13, v119, v87
	ds_write_b32 v4, v13 offset:792
	s_waitcnt vmcnt(27)
	v_mul_f32_e32 v13, v120, v88
	ds_write_b32 v4, v13 offset:1056
	s_waitcnt vmcnt(26)
	v_mul_f32_e32 v13, v121, v89
	ds_write_b32 v4, v13 offset:1320
	s_waitcnt vmcnt(25)
	v_mul_f32_e32 v13, v122, v90
	ds_write_b32 v4, v13 offset:1584
	s_waitcnt vmcnt(24)
	v_mul_f32_e32 v13, v123, v91
	ds_write_b32 v4, v13 offset:1848
	s_waitcnt vmcnt(23)
	v_mul_f32_e32 v13, v124, v92
	ds_write_b32 v4, v13 offset:2112
	s_waitcnt vmcnt(22)
	v_mul_f32_e32 v13, v125, v93
	ds_write_b32 v4, v13 offset:2376
	s_waitcnt vmcnt(21)
	v_mul_f32_e32 v13, v126, v94
	ds_write_b32 v4, v13 offset:2640
	s_waitcnt vmcnt(20)
	v_mul_f32_e32 v13, v127, v95
	ds_write_b32 v4, v13 offset:2904
	s_waitcnt vmcnt(19)
	v_mul_f32_e32 v13, v128, v96
	ds_write_b32 v4, v13 offset:3168
	s_waitcnt vmcnt(18)
	v_mul_f32_e32 v13, v129, v97
	ds_write_b32 v4, v13 offset:3432
	s_waitcnt vmcnt(17)
	v_mul_f32_e32 v13, v130, v98
	ds_write_b32 v4, v13 offset:3696
	s_waitcnt vmcnt(16)
	v_mul_f32_e32 v13, v131, v99
	ds_write_b32 v4, v13 offset:3960
	s_waitcnt vmcnt(15)
	v_mul_f32_e32 v13, v132, v100
	ds_write_b32 v4, v13 offset:4224
	s_waitcnt vmcnt(14)
	v_mul_f32_e32 v13, v133, v101
	ds_write_b32 v4, v13 offset:4488
	s_waitcnt vmcnt(13)
	v_mul_f32_e32 v13, v134, v102
	ds_write_b32 v4, v13 offset:4752
	s_waitcnt vmcnt(12)
	v_mul_f32_e32 v13, v135, v103
	ds_write_b32 v4, v13 offset:5016
	s_waitcnt vmcnt(11)
	v_mul_f32_e32 v13, v136, v104
	ds_write_b32 v4, v13 offset:5280
	s_waitcnt vmcnt(10)
	v_mul_f32_e32 v13, v137, v105
	ds_write_b32 v4, v13 offset:5544
	s_waitcnt vmcnt(9)
	v_mul_f32_e32 v13, v138, v106
	ds_write_b32 v4, v13 offset:5808
	s_waitcnt vmcnt(8)
	v_mul_f32_e32 v13, v139, v107
	ds_write_b32 v4, v13 offset:6072
	s_waitcnt vmcnt(7)
	v_mul_f32_e32 v13, v140, v108
	ds_write_b32 v4, v13 offset:6336
	s_waitcnt vmcnt(6)
	v_mul_f32_e32 v13, v141, v109
	ds_write_b32 v4, v13 offset:6600
	s_waitcnt vmcnt(5)
	v_mul_f32_e32 v13, v142, v110
	ds_write_b32 v4, v13 offset:6864
	s_waitcnt vmcnt(4)
	v_mul_f32_e32 v13, v143, v111
	ds_write_b32 v4, v13 offset:7128
	s_waitcnt vmcnt(3)
	v_mul_f32_e32 v13, v144, v112
	ds_write_b32 v4, v13 offset:7392
	s_waitcnt vmcnt(2)
	v_mul_f32_e32 v13, v145, v113
	ds_write_b32 v4, v13 offset:7656
	s_waitcnt vmcnt(1)
	v_mul_f32_e32 v13, v146, v114
	ds_write_b32 v4, v13 offset:7920
	s_waitcnt vmcnt(0)
	v_mul_f32_e32 v13, v147, v115
	ds_write_b32 v4, v13 offset:8184
	s_branch .LBB0_18
